# final f32 out stores: fq row pairs exchange one quad (v_permlane16_swap) so each store writes 32 B contiguous instead of 16 B pieces (24 of 32 stores)
# speedup vs baseline: 1.0081x; 1.0026x over previous
;     __device__ __forceinline__ void fused(f32x4 (&acc)[2][2][4][2], const pg8::Unit& u, int wr, int wc, int fr, int fq, LAS unsigned char* lds, int wid, int lane) const {
;     ...
;         f32x4 pw[2][2];
; #pragma unroll
;         for (int bj = 0; bj < 2; ++bj) { pw[bj][0] = *(const f32x4*)(post_w + col0 + bj * 128); pw[bj][1] = *(const f32x4*)(post_w + col0 + bj * 128 + 4); }
; #pragma unroll
;         for (int ai = 0; ai < 2; ++ai) {
;             if (ai == 1) {
; #pragma unroll
;                 for (int m = 0; m < 4; ++m)
; #pragma unroll
;                     for (int bj = 0; bj < 2; ++bj) { xv[m][bj][0] = __builtin_nontemporal_load((const f32x4*)(x + off0 + (size_t)(128 + m * 16) * 1024 + bj * 128)); xv[m][bj][1] = __builtin_nontemporal_load((const f32x4*)(x + off0 + (size_t)(128 + m * 16) * 1024 + bj * 128 + 4)); }
;             }
; #pragma unroll
;             for (int m = 0; m < 4; ++m) {
;                 const int lr = ai * 128 + wr * 64 + m * 16 + fr; const float rs = S[lr];
;                 const size_t off = off0 + (size_t)(ai * 128 + m * 16) * 1024;
; #pragma unroll
;                 for (int bj = 0; bj < 2; ++bj) {
;                     *(f32x4*)(out + off + bj * 128) = xv[m][bj][0] + acc[ai][bj][m][0] * rs * pw[bj][0];
;                     *(f32x4*)(out + off + bj * 128 + 4) = xv[m][bj][1] + acc[ai][bj][m][1] * rs * pw[bj][1];
;                 }
;             }
.LBB0_911:
	s_or_b64 exec, exec, s[4:5]
	v_lshl_add_u64 v[192:193], v[192:193], 2, s[72:73]
	s_waitcnt lgkmcnt(0)
	s_barrier
	global_load_dwordx4 v[204:207], v[192:193], off
	global_load_dwordx4 v[200:203], v[192:193], off offset:16
	global_load_dwordx4 v[196:199], v[192:193], off offset:512
	s_nop 0
	global_load_dwordx4 v[192:195], v[192:193], off offset:528
	s_lshl_b32 s2, s34, 2
	s_add_i32 s2, s2, 0
	v_lshl_add_u32 v213, v213, 2, s2
	v_add_u32_e32 v213, 0x1000, v213
	ds_read2_b32 v[216:217], v213 offset1:16
	ds_read2_b32 v[220:221], v213 offset0:32 offset1:48
	v_lshl_add_u64 v[210:211], v[210:211], 2, s[74:75]
	s_mov_b32 s3, 0x10000
	v_add_co_u32_e32 v214, vcc, s3, v210
	s_mov_b32 s4, 0x20000
	s_nop 0
	v_addc_co_u32_e32 v215, vcc, 0, v211, vcc
	s_waitcnt lgkmcnt(1)
	v_pk_mul_f32 v[126:127], v[126:127], v[216:217] op_sel_hi:[1,0]
	v_pk_mul_f32 v[124:125], v[124:125], v[216:217] op_sel_hi:[1,0]
	v_pk_mul_f32 v[122:123], v[122:123], v[216:217] op_sel_hi:[1,0]
	v_pk_mul_f32 v[120:121], v[120:121], v[216:217] op_sel_hi:[1,0]
	v_pk_mul_f32 v[110:111], v[110:111], v[216:217] op_sel_hi:[1,0]
	v_pk_mul_f32 v[108:109], v[108:109], v[216:217] op_sel_hi:[1,0]
	v_pk_mul_f32 v[106:107], v[106:107], v[216:217] op_sel_hi:[1,0]
	v_pk_mul_f32 v[104:105], v[104:105], v[216:217] op_sel_hi:[1,0]
	v_mov_b32_e32 v216, v217
	v_add_co_u32_e32 v218, vcc, s4, v210
	s_waitcnt lgkmcnt(0)
	v_pk_mul_f32 v[118:119], v[118:119], v[220:221] op_sel_hi:[1,0]
	v_pk_mul_f32 v[116:117], v[116:117], v[220:221] op_sel_hi:[1,0]
	v_pk_mul_f32 v[222:223], v[114:115], v[220:221] op_sel_hi:[1,0]
	v_pk_mul_f32 v[224:225], v[112:113], v[220:221] op_sel_hi:[1,0]
	v_pk_mul_f32 v[226:227], v[94:95], v[220:221] op_sel_hi:[1,0]
	v_pk_mul_f32 v[228:229], v[92:93], v[220:221] op_sel_hi:[1,0]
	v_pk_mul_f32 v[230:231], v[82:83], v[220:221] op_sel_hi:[1,0]
	v_pk_mul_f32 v[232:233], v[80:81], v[220:221] op_sel_hi:[1,0]
	v_pk_mul_f32 v[102:103], v[102:103], v[216:217] op_sel_hi:[1,0]
	v_pk_mul_f32 v[100:101], v[100:101], v[216:217] op_sel_hi:[1,0]
	v_pk_mul_f32 v[112:113], v[98:99], v[216:217] op_sel_hi:[1,0]
	v_pk_mul_f32 v[114:115], v[96:97], v[216:217] op_sel_hi:[1,0]
	v_pk_mul_f32 v[234:235], v[90:91], v[216:217] op_sel_hi:[1,0]
	v_pk_mul_f32 v[236:237], v[88:89], v[216:217] op_sel_hi:[1,0]
	v_pk_mul_f32 v[238:239], v[86:87], v[216:217] op_sel_hi:[1,0]
	v_pk_mul_f32 v[216:217], v[84:85], v[216:217] op_sel_hi:[1,0]
	v_addc_co_u32_e32 v219, vcc, 0, v211, vcc
	s_mov_b32 s2, 0x30000
	s_mov_b32 s8, 0x80000
	s_mov_b32 s9, 0x90000
	s_mov_b32 s10, 0xa0000
	s_mov_b64 s[4:5], 0xa0000
	s_waitcnt vmcnt(3)
	v_pk_fma_f32 v[82:83], v[206:207], v[126:127], v[162:163]
	v_pk_fma_f32 v[80:81], v[204:205], v[124:125], v[160:161]
	s_waitcnt vmcnt(2)
	v_pk_fma_f32 v[86:87], v[202:203], v[122:123], v[154:155]
	v_pk_fma_f32 v[84:85], v[200:201], v[120:121], v[152:153]
	s_waitcnt vmcnt(1)
	v_pk_fma_f32 v[90:91], v[198:199], v[110:111], v[158:159]
	v_pk_fma_f32 v[88:89], v[196:197], v[108:109], v[156:157]
	s_waitcnt vmcnt(0)
	v_pk_fma_f32 v[94:95], v[194:195], v[106:107], v[150:151]
	v_pk_fma_f32 v[92:93], v[192:193], v[104:105], v[148:149]
	v_pk_fma_f32 v[98:99], v[206:207], v[102:103], v[178:179]
	v_pk_fma_f32 v[96:97], v[204:205], v[100:101], v[176:177]
	v_pk_fma_f32 v[102:103], v[202:203], v[112:113], v[166:167]
	v_pk_fma_f32 v[100:101], v[200:201], v[114:115], v[164:165]
	v_pk_fma_f32 v[106:107], v[198:199], v[234:235], v[174:175]
	v_pk_fma_f32 v[104:105], v[196:197], v[236:237], v[172:173]
	v_pk_fma_f32 v[110:111], v[194:195], v[238:239], v[170:171]
	v_pk_fma_f32 v[108:109], v[192:193], v[216:217], v[168:169]
	v_pk_fma_f32 v[114:115], v[206:207], v[118:119], v[190:191]
	v_pk_fma_f32 v[112:113], v[204:205], v[116:117], v[188:189]
	v_pk_fma_f32 v[118:119], v[202:203], v[222:223], v[182:183]
	v_pk_fma_f32 v[116:117], v[200:201], v[224:225], v[180:181]
	v_pk_fma_f32 v[122:123], v[198:199], v[226:227], v[186:187]
	v_pk_fma_f32 v[120:121], v[196:197], v[228:229], v[184:185]
	v_mbcnt_lo_u32_b32 v250, -1, 0
	v_mbcnt_hi_u32_b32 v250, -1, v250
	v_and_b32_e32 v250, 16, v250
	v_sub_u32_e32 v250, 0, v250
	v_ashrrev_i32_e32 v251, 31, v250
	v_lshl_add_u64 v[252:253], v[210:211], 0, v[250:251]
	v_permlane16_swap_b32 v80, v84
	v_permlane16_swap_b32 v81, v85
	v_permlane16_swap_b32 v82, v86
	v_permlane16_swap_b32 v83, v87
	v_permlane16_swap_b32 v88, v92
	v_permlane16_swap_b32 v89, v93
	v_permlane16_swap_b32 v90, v94
	v_permlane16_swap_b32 v91, v95
	s_nop 0
	global_store_dwordx4 v[252:253], v[80:83], off
	global_store_dwordx4 v[252:253], v[84:87], off offset:32
	global_store_dwordx4 v[252:253], v[88:91], off offset:512
	global_store_dwordx4 v[252:253], v[92:95], off offset:544
	v_lshl_add_u64 v[252:253], v[214:215], 0, v[250:251]
	v_permlane16_swap_b32 v96, v100
	v_permlane16_swap_b32 v97, v101
	v_permlane16_swap_b32 v98, v102
	v_permlane16_swap_b32 v99, v103
	v_permlane16_swap_b32 v104, v108
	v_permlane16_swap_b32 v105, v109
	v_permlane16_swap_b32 v106, v110
	v_permlane16_swap_b32 v107, v111
	s_nop 0
	global_store_dwordx4 v[252:253], v[96:99], off
	global_store_dwordx4 v[252:253], v[100:103], off offset:32
	global_store_dwordx4 v[252:253], v[104:107], off offset:512
	global_store_dwordx4 v[252:253], v[108:111], off offset:544
	v_lshl_add_u64 v[252:253], v[218:219], 0, v[250:251]
	v_permlane16_swap_b32 v112, v116
	v_permlane16_swap_b32 v113, v117
	v_permlane16_swap_b32 v114, v118
	v_permlane16_swap_b32 v115, v119
	s_nop 0
	global_store_dwordx4 v[252:253], v[112:115], off
	global_store_dwordx4 v[252:253], v[116:119], off offset:32
	v_pk_fma_f32 v[82:83], v[194:195], v[230:231], v[146:147]
	v_pk_fma_f32 v[80:81], v[192:193], v[232:233], v[144:145]
;     __device__ __forceinline__ void fused(f32x4 (&acc)[2][2][4][2], const pg8::Unit& u, int wr, int wc, int fr, int fq, LAS unsigned char* lds, int wid, int lane) const {
;     ...
;         for (int ai = 0; ai < 2; ++ai) {
;             if (ai == 1) {
; #pragma unroll
;                 for (int m = 0; m < 4; ++m)
; #pragma unroll
;                     for (int bj = 0; bj < 2; ++bj) { xv[m][bj][0] = __builtin_nontemporal_load((const f32x4*)(x + off0 + (size_t)(128 + m * 16) * 1024 + bj * 128)); xv[m][bj][1] = __builtin_nontemporal_load((const f32x4*)(x + off0 + (size_t)(128 + m * 16) * 1024 + bj * 128 + 4)); }
;             }
; #pragma unroll
;             for (int m = 0; m < 4; ++m) {
;                 const int lr = ai * 128 + wr * 64 + m * 16 + fr; const float rs = S[lr];
;                 const size_t off = off0 + (size_t)(ai * 128 + m * 16) * 1024;
; #pragma unroll
;                 for (int bj = 0; bj < 2; ++bj) {
;                     *(f32x4*)(out + off + bj * 128) = xv[m][bj][0] + acc[ai][bj][m][0] * rs * pw[bj][0];
;                     *(f32x4*)(out + off + bj * 128 + 4) = xv[m][bj][1] + acc[ai][bj][m][1] * rs * pw[bj][1];
;                 }
;             }
	s_nop 1
	v_permlane16_swap_b32 v120, v80
	v_permlane16_swap_b32 v121, v81
	v_permlane16_swap_b32 v122, v82
	v_permlane16_swap_b32 v123, v83
	s_nop 0
	global_store_dwordx4 v[252:253], v[120:123], off offset:512
	global_store_dwordx4 v[252:253], v[80:83], off offset:544
	s_nop 1
	v_lshl_add_u64 v[104:105], v[208:209], 0, s[4:5]
	s_mov_b64 s[4:5], 0xb0000
	v_mov_b32_e32 v80, v221
	v_pk_mul_f32 v[78:79], v[78:79], v[80:81] op_sel_hi:[1,0]
	v_pk_mul_f32 v[76:77], v[76:77], v[80:81] op_sel_hi:[1,0]
	v_add_co_u32_e32 v82, vcc, s2, v210
	v_pk_mul_f32 v[74:75], v[74:75], v[80:81] op_sel_hi:[1,0]
	v_pk_mul_f32 v[72:73], v[72:73], v[80:81] op_sel_hi:[1,0]
	v_pk_mul_f32 v[70:71], v[70:71], v[80:81] op_sel_hi:[1,0]
	v_pk_mul_f32 v[68:69], v[68:69], v[80:81] op_sel_hi:[1,0]
	v_pk_mul_f32 v[66:67], v[66:67], v[80:81] op_sel_hi:[1,0]
	v_pk_mul_f32 v[64:65], v[64:65], v[80:81] op_sel_hi:[1,0]
	v_pk_fma_f32 v[78:79], v[206:207], v[78:79], v[142:143]
	v_pk_fma_f32 v[76:77], v[204:205], v[76:77], v[140:141]
	v_addc_co_u32_e32 v83, vcc, 0, v211, vcc
	v_pk_fma_f32 v[74:75], v[202:203], v[74:75], v[138:139]
	v_pk_fma_f32 v[72:73], v[200:201], v[72:73], v[136:137]
	v_pk_fma_f32 v[70:71], v[198:199], v[70:71], v[134:135]
	v_pk_fma_f32 v[68:69], v[196:197], v[68:69], v[132:133]
	v_pk_fma_f32 v[66:67], v[194:195], v[66:67], v[130:131]
	v_pk_fma_f32 v[64:65], v[192:193], v[64:65], v[128:129]
	s_nop 1
	v_lshl_add_u64 v[252:253], v[82:83], 0, v[250:251]
	v_permlane16_swap_b32 v76, v72
	v_permlane16_swap_b32 v77, v73
	v_permlane16_swap_b32 v78, v74
	v_permlane16_swap_b32 v79, v75
	v_permlane16_swap_b32 v68, v64
	v_permlane16_swap_b32 v69, v65
	v_permlane16_swap_b32 v70, v66
	v_permlane16_swap_b32 v71, v67
	s_nop 0
	global_store_dwordx4 v[252:253], v[76:79], off
	global_store_dwordx4 v[252:253], v[72:75], off offset:32
	global_store_dwordx4 v[252:253], v[68:71], off offset:512
	global_store_dwordx4 v[252:253], v[64:67], off offset:544
	s_nop 1
	v_add_co_u32_e32 v76, vcc, s8, v208
	s_mov_b64 s[2:3], 0x80000
	s_nop 0
	v_addc_co_u32_e32 v77, vcc, 0, v209, vcc
	global_load_dwordx4 v[64:67], v[76:77], off nt
	v_lshl_add_u64 v[78:79], v[208:209], 0, s[2:3]
	s_mov_b64 s[2:3], 0x80200
	global_load_dwordx4 v[68:71], v[78:79], off offset:16 nt
	global_load_dwordx4 v[72:75], v[76:77], off offset:512 nt
	v_lshl_add_u64 v[76:77], v[208:209], 0, s[2:3]
	global_load_dwordx4 v[76:79], v[76:77], off offset:16 nt
	v_add_co_u32_e32 v92, vcc, s9, v208
	s_mov_b64 s[2:3], 0x90000
	s_nop 0
	v_addc_co_u32_e32 v93, vcc, 0, v209, vcc
	global_load_dwordx4 v[80:83], v[92:93], off nt
	v_lshl_add_u64 v[94:95], v[208:209], 0, s[2:3]
	global_load_dwordx4 v[84:87], v[94:95], off offset:16 nt
	global_load_dwordx4 v[88:91], v[92:93], off offset:512 nt
	s_mov_b64 s[2:3], 0x90200
	v_lshl_add_u64 v[92:93], v[208:209], 0, s[2:3]
	global_load_dwordx4 v[92:95], v[92:93], off offset:16 nt
	v_add_co_u32_e32 v100, vcc, s10, v208
	s_mov_b64 s[2:3], 0xa0200
	s_nop 0
	v_addc_co_u32_e32 v101, vcc, 0, v209, vcc
	global_load_dwordx4 v[96:99], v[100:101], off nt
	v_lshl_add_u64 v[108:109], v[208:209], 0, s[2:3]
	s_mov_b64 s[2:3], 0xb0200
	global_load_dwordx4 v[100:103], v[100:101], off offset:512 nt
	s_nop 0
	global_load_dwordx4 v[104:107], v[104:105], off offset:16 nt
	v_lshl_add_u64 v[112:113], v[208:209], 0, s[2:3]
	global_load_dwordx4 v[108:111], v[108:109], off offset:16 nt
	s_mov_b32 s2, 0xb0000
	v_add_co_u32_e32 v120, vcc, s2, v208
	v_lshl_add_u64 v[124:125], v[208:209], 0, s[4:5]
	s_nop 0
	v_addc_co_u32_e32 v121, vcc, 0, v209, vcc
	ds_read2_b32 v[128:129], v213 offset0:128 offset1:144
	global_load_dwordx4 v[112:115], v[112:113], off offset:16 nt
	s_nop 0
	global_load_dwordx4 v[116:119], v[120:121], off nt
	s_nop 0
	global_load_dwordx4 v[120:123], v[120:121], off offset:512 nt
	s_nop 0
	global_load_dwordx4 v[124:127], v[124:125], off offset:16 nt
	s_waitcnt lgkmcnt(0)
	v_pk_mul_f32 v[60:61], v[60:61], v[128:129] op_sel_hi:[1,0]
	v_pk_mul_f32 v[50:51], v[50:51], v[128:129] op_sel_hi:[1,0]
	v_pk_mul_f32 v[48:49], v[48:49], v[128:129] op_sel_hi:[1,0]
	v_pk_mul_f32 v[46:47], v[46:47], v[128:129] op_sel_hi:[1,0]
	v_pk_mul_f32 v[44:45], v[44:45], v[128:129] op_sel_hi:[1,0]
	v_pk_mul_f32 v[62:63], v[62:63], v[128:129] op_sel_hi:[1,0]
	v_pk_mul_f32 v[58:59], v[58:59], v[128:129] op_sel_hi:[1,0]
	v_pk_mul_f32 v[56:57], v[56:57], v[128:129] op_sel_hi:[1,0]
	s_waitcnt vmcnt(15)
	v_pk_fma_f32 v[60:61], v[204:205], v[60:61], v[64:65]
	v_add_co_u32_e32 v64, vcc, s8, v210
	s_waitcnt vmcnt(13)
	v_pk_fma_f32 v[50:51], v[198:199], v[50:51], v[74:75]
	v_addc_co_u32_e32 v65, vcc, 0, v211, vcc
	v_pk_fma_f32 v[48:49], v[196:197], v[48:49], v[72:73]
	global_store_dwordx4 v[64:65], v[48:51], off offset:512
	s_waitcnt vmcnt(13)
;     __device__ __forceinline__ void fused(f32x4 (&acc)[2][2][4][2], const pg8::Unit& u, int wr, int wc, int fr, int fq, LAS unsigned char* lds, int wid, int lane) const {
;     ...
;             if (ai == 1) {
; #pragma unroll
;                 for (int m = 0; m < 4; ++m)
; #pragma unroll
;                     for (int bj = 0; bj < 2; ++bj) { xv[m][bj][0] = __builtin_nontemporal_load((const f32x4*)(x + off0 + (size_t)(128 + m * 16) * 1024 + bj * 128)); xv[m][bj][1] = __builtin_nontemporal_load((const f32x4*)(x + off0 + (size_t)(128 + m * 16) * 1024 + bj * 128 + 4)); }
;             }
; #pragma unroll
;             for (int m = 0; m < 4; ++m) {
;                 const int lr = ai * 128 + wr * 64 + m * 16 + fr; const float rs = S[lr];
;                 const size_t off = off0 + (size_t)(ai * 128 + m * 16) * 1024;
; #pragma unroll
;                 for (int bj = 0; bj < 2; ++bj) {
;                     *(f32x4*)(out + off + bj * 128) = xv[m][bj][0] + acc[ai][bj][m][0] * rs * pw[bj][0];
;                     *(f32x4*)(out + off + bj * 128 + 4) = xv[m][bj][1] + acc[ai][bj][m][1] * rs * pw[bj][1];
;                 }
;             }
	v_pk_fma_f32 v[46:47], v[194:195], v[46:47], v[78:79]
	v_pk_fma_f32 v[44:45], v[192:193], v[44:45], v[76:77]
	v_mov_b32_e32 v48, v129
	global_store_dwordx4 v[64:65], v[44:47], off offset:528
	v_pk_mul_f32 v[50:51], v[52:53], v[48:49] op_sel_hi:[1,0]
	v_pk_mul_f32 v[38:39], v[38:39], v[48:49] op_sel_hi:[1,0]
	v_pk_mul_f32 v[44:45], v[54:55], v[48:49] op_sel_hi:[1,0]
	v_pk_mul_f32 v[36:37], v[36:37], v[48:49] op_sel_hi:[1,0]
	s_waitcnt vmcnt(13)
	v_pk_fma_f32 v[46:47], v[206:207], v[44:45], v[82:83]
	v_pk_fma_f32 v[44:45], v[204:205], v[50:51], v[80:81]
	v_add_co_u32_e32 v50, vcc, s9, v210
	s_waitcnt vmcnt(11)
	v_pk_fma_f32 v[38:39], v[198:199], v[38:39], v[90:91]
	v_addc_co_u32_e32 v51, vcc, 0, v211, vcc
	v_pk_fma_f32 v[36:37], v[196:197], v[36:37], v[88:89]
	global_store_dwordx4 v[50:51], v[36:39], off offset:512
	ds_read2_b32 v[36:37], v213 offset0:160 offset1:176
	v_pk_mul_f32 v[26:27], v[26:27], v[48:49] op_sel_hi:[1,0]
	v_pk_mul_f32 v[24:25], v[24:25], v[48:49] op_sel_hi:[1,0]
	s_waitcnt vmcnt(11)
	v_pk_fma_f32 v[26:27], v[194:195], v[26:27], v[94:95]
	v_pk_fma_f32 v[24:25], v[192:193], v[24:25], v[92:93]
	global_store_dwordx4 v[50:51], v[24:27], off offset:528
	s_waitcnt lgkmcnt(0)
	v_pk_mul_f32 v[32:33], v[32:33], v[36:37] op_sel_hi:[1,0]
	v_pk_mul_f32 v[18:19], v[18:19], v[36:37] op_sel_hi:[1,0]
	v_pk_mul_f32 v[24:25], v[34:35], v[36:37] op_sel_hi:[1,0]
	v_pk_mul_f32 v[16:17], v[16:17], v[36:37] op_sel_hi:[1,0]
	s_waitcnt vmcnt(11)
	v_pk_fma_f32 v[26:27], v[206:207], v[24:25], v[98:99]
	v_pk_fma_f32 v[24:25], v[204:205], v[32:33], v[96:97]
	v_add_co_u32_e32 v32, vcc, s10, v210
	s_waitcnt vmcnt(10)
	v_pk_fma_f32 v[18:19], v[198:199], v[18:19], v[102:103]
	v_addc_co_u32_e32 v33, vcc, 0, v211, vcc
	v_pk_fma_f32 v[16:17], v[196:197], v[16:17], v[100:101]
	v_pk_mul_f32 v[14:15], v[14:15], v[36:37] op_sel_hi:[1,0]
	v_pk_mul_f32 v[12:13], v[12:13], v[36:37] op_sel_hi:[1,0]
	global_store_dwordx4 v[32:33], v[16:19], off offset:512
	s_waitcnt vmcnt(9)
	v_pk_fma_f32 v[14:15], v[194:195], v[14:15], v[110:111]
	v_pk_fma_f32 v[12:13], v[192:193], v[12:13], v[108:109]
	v_mov_b32_e32 v16, v37
	global_store_dwordx4 v[32:33], v[12:15], off offset:528
	v_pk_mul_f32 v[18:19], v[20:21], v[16:17] op_sel_hi:[1,0]
	v_pk_mul_f32 v[42:43], v[42:43], v[48:49] op_sel_hi:[1,0]
	v_pk_mul_f32 v[12:13], v[22:23], v[16:17] op_sel_hi:[1,0]
	v_pk_mul_f32 v[40:41], v[40:41], v[48:49] op_sel_hi:[1,0]
	global_store_dwordx4 v[32:33], v[24:27], off
	v_pk_mul_f32 v[28:29], v[28:29], v[36:37] op_sel_hi:[1,0]
	s_waitcnt vmcnt(9)
	v_pk_fma_f32 v[14:15], v[206:207], v[12:13], v[118:119]
	v_pk_mul_f32 v[24:25], v[30:31], v[36:37] op_sel_hi:[1,0]
	v_pk_fma_f32 v[12:13], v[204:205], v[18:19], v[116:117]
	v_add_co_u32_e32 v18, vcc, s2, v210
	v_pk_mul_f32 v[10:11], v[10:11], v[16:17] op_sel_hi:[1,0]
	v_pk_mul_f32 v[8:9], v[8:9], v[16:17] op_sel_hi:[1,0]
	v_pk_mul_f32 v[6:7], v[6:7], v[16:17] op_sel_hi:[1,0]
	v_pk_mul_f32 v[4:5], v[4:5], v[16:17] op_sel_hi:[1,0]
	v_pk_mul_f32 v[2:3], v[2:3], v[16:17] op_sel_hi:[1,0]
	v_pk_mul_f32 v[0:1], v[0:1], v[16:17] op_sel_hi:[1,0]
	v_pk_fma_f32 v[62:63], v[206:207], v[62:63], v[66:67]
	v_pk_fma_f32 v[58:59], v[202:203], v[58:59], v[70:71]
	v_pk_fma_f32 v[56:57], v[200:201], v[56:57], v[68:69]
	v_pk_fma_f32 v[42:43], v[202:203], v[42:43], v[86:87]
	v_pk_fma_f32 v[40:41], v[200:201], v[40:41], v[84:85]
	v_pk_fma_f32 v[26:27], v[202:203], v[24:25], v[106:107]
	v_pk_fma_f32 v[24:25], v[200:201], v[28:29], v[104:105]
	v_addc_co_u32_e32 v19, vcc, 0, v211, vcc
	s_waitcnt vmcnt(7)
	v_pk_fma_f32 v[10:11], v[202:203], v[10:11], v[126:127]
	v_pk_fma_f32 v[8:9], v[200:201], v[8:9], v[124:125]
	v_pk_fma_f32 v[6:7], v[198:199], v[6:7], v[122:123]
	v_pk_fma_f32 v[4:5], v[196:197], v[4:5], v[120:121]
	v_pk_fma_f32 v[2:3], v[194:195], v[2:3], v[114:115]
	v_pk_fma_f32 v[0:1], v[192:193], v[0:1], v[112:113]
	s_nop 1
	v_lshl_add_u64 v[252:253], v[64:65], 0, v[250:251]
	v_permlane16_swap_b32 v60, v56
	v_permlane16_swap_b32 v61, v57
	v_permlane16_swap_b32 v62, v58
	v_permlane16_swap_b32 v63, v59
	s_nop 0
	global_store_dwordx4 v[252:253], v[60:63], off
	global_store_dwordx4 v[252:253], v[56:59], off offset:32
	v_lshl_add_u64 v[252:253], v[50:51], 0, v[250:251]
	v_permlane16_swap_b32 v44, v40
	v_permlane16_swap_b32 v45, v41
	v_permlane16_swap_b32 v46, v42
	v_permlane16_swap_b32 v47, v43
	s_nop 0
	global_store_dwordx4 v[252:253], v[44:47], off
	global_store_dwordx4 v[252:253], v[40:43], off offset:32
	global_store_dwordx4 v[32:33], v[24:27], off offset:16
	v_lshl_add_u64 v[252:253], v[18:19], 0, v[250:251]
	v_permlane16_swap_b32 v12, v8
	v_permlane16_swap_b32 v13, v9
	v_permlane16_swap_b32 v14, v10
	v_permlane16_swap_b32 v15, v11
	v_permlane16_swap_b32 v4, v0
	v_permlane16_swap_b32 v5, v1
	v_permlane16_swap_b32 v6, v2
	v_permlane16_swap_b32 v7, v3
	s_nop 0
	global_store_dwordx4 v[252:253], v[12:15], off
	global_store_dwordx4 v[252:253], v[8:11], off offset:32
	global_store_dwordx4 v[252:253], v[4:7], off offset:512
	global_store_dwordx4 v[252:253], v[0:3], off offset:544
